# phase0 bias1: 16 blocks x 8 waves split-K with 32 loads in flight + LDS reduce (was 4 blocks x 2048 dependent steps)
# speedup vs baseline: 1.1582x; 1.0077x over previous
; #define TIDX get_tid_()
; DI void phase0(const Params& p, char* lds) {
;     ...
;   for (int it = blockIdx.x; it < 4; it += gridDim.x) {
;     const int l = it >> 1, kv = it & 1;
;     const float* pe = p.in[kv ? I_PEV : I_PEK] + (size_t)l * 2048;
;     const float* w = p.in[kv ? I_PV1 : I_PK1] + (size_t)l * 2048 * 256;
;     const int n = TIDX;
;     if (n < 256) {
;       float s = 0.f;
;       for (int k = 0; k < 2048; ++k) s += pe[k] * w[(size_t)k * 256 + n];
;       ((float*)(p.ws + OFF_MISC + 256))[it * 256 + n] = s;
;     }
;   }
.LBB0_772:
	v_readlane_b32 s4, v254, 1
	v_readlane_b32 s24, v254, 46
	v_readlane_b32 s25, v254, 47
	v_lshrrev_b32_e32 v0, 6, v129
	s_nop 3
	s_cmp_gt_u32 s4, 15
	s_cbranch_scc1 .LBB0_773
	v_readfirstlane_b32 s15, v0
	s_lshr_b32 s8, s4, 2
	s_and_b32 s26, s8, 1
	s_lshr_b32 s14, s8, 1
	s_lshl_b32 s9, s26, 3
	s_add_u32 s9, s9, 0x40
	s_load_dwordx2 s[22:23], s[24:25], s9
	s_lshl_b32 s9, s26, 4
	s_add_u32 s9, s9, 0x50
	s_load_dwordx2 s[10:11], s[24:25], s9
	s_lshl_b32 s54, s14, 13
	s_lshl_b32 s55, s15, 10
	s_add_u32 s54, s54, s55
	s_waitcnt lgkmcnt(0)
	s_add_u32 s22, s22, s54
	s_addc_u32 s23, s23, 0
	s_lshl_b32 s54, s14, 21
	s_lshl_b32 s55, s15, 18
	s_add_u32 s54, s54, s55
	s_and_b32 s55, s4, 3
	s_lshl_b32 s55, s55, 8
	s_add_u32 s54, s54, s55
	s_add_u32 s10, s10, s54
	s_addc_u32 s11, s11, 0
	v_and_b32_e32 v0, 63, v129
	v_lshlrev_b32_e32 v0, 2, v0
	v_mov_b32_e32 v1, 0
	s_mov_b32 s26, 8
.Lb1_loop:
	global_load_dwordx4 v[8:11], v131, s[22:23] offset:0
	global_load_dwordx4 v[12:15], v131, s[22:23] offset:16
	global_load_dwordx4 v[16:19], v131, s[22:23] offset:32
	global_load_dwordx4 v[20:23], v131, s[22:23] offset:48
	global_load_dwordx4 v[24:27], v131, s[22:23] offset:64
	global_load_dwordx4 v[28:31], v131, s[22:23] offset:80
	global_load_dwordx4 v[32:35], v131, s[22:23] offset:96
	global_load_dwordx4 v[36:39], v131, s[22:23] offset:112
	global_load_dword v40, v0, s[10:11] offset:0
	global_load_dword v41, v0, s[10:11] offset:1024
	global_load_dword v42, v0, s[10:11] offset:2048
	global_load_dword v43, v0, s[10:11] offset:3072
	s_add_u32 s10, s10, 0x1000
	s_addc_u32 s11, s11, 0
	global_load_dword v44, v0, s[10:11] offset:0
	global_load_dword v45, v0, s[10:11] offset:1024
	global_load_dword v46, v0, s[10:11] offset:2048
	global_load_dword v47, v0, s[10:11] offset:3072
	s_add_u32 s10, s10, 0x1000
	s_addc_u32 s11, s11, 0
	global_load_dword v48, v0, s[10:11] offset:0
	global_load_dword v49, v0, s[10:11] offset:1024
	global_load_dword v50, v0, s[10:11] offset:2048
	global_load_dword v51, v0, s[10:11] offset:3072
	s_add_u32 s10, s10, 0x1000
	s_addc_u32 s11, s11, 0
	global_load_dword v52, v0, s[10:11] offset:0
	global_load_dword v53, v0, s[10:11] offset:1024
	global_load_dword v54, v0, s[10:11] offset:2048
	global_load_dword v55, v0, s[10:11] offset:3072
	s_add_u32 s10, s10, 0x1000
	s_addc_u32 s11, s11, 0
	global_load_dword v56, v0, s[10:11] offset:0
	global_load_dword v57, v0, s[10:11] offset:1024
	global_load_dword v58, v0, s[10:11] offset:2048
	global_load_dword v59, v0, s[10:11] offset:3072
	s_add_u32 s10, s10, 0x1000
	s_addc_u32 s11, s11, 0
	global_load_dword v60, v0, s[10:11] offset:0
	global_load_dword v61, v0, s[10:11] offset:1024
	global_load_dword v62, v0, s[10:11] offset:2048
	global_load_dword v63, v0, s[10:11] offset:3072
	s_add_u32 s10, s10, 0x1000
	s_addc_u32 s11, s11, 0
	global_load_dword v64, v0, s[10:11] offset:0
	global_load_dword v65, v0, s[10:11] offset:1024
	global_load_dword v66, v0, s[10:11] offset:2048
	global_load_dword v67, v0, s[10:11] offset:3072
	s_add_u32 s10, s10, 0x1000
	s_addc_u32 s11, s11, 0
	global_load_dword v68, v0, s[10:11] offset:0
	global_load_dword v69, v0, s[10:11] offset:1024
	global_load_dword v70, v0, s[10:11] offset:2048
	global_load_dword v71, v0, s[10:11] offset:3072
	s_add_u32 s10, s10, 0x1000
	s_addc_u32 s11, s11, 0
	s_add_u32 s22, s22, 0x80
	s_addc_u32 s23, s23, 0
	s_waitcnt vmcnt(0)
	v_fmac_f32_e32 v1, v8, v40
	v_fmac_f32_e32 v1, v9, v41
	v_fmac_f32_e32 v1, v10, v42
	v_fmac_f32_e32 v1, v11, v43
	v_fmac_f32_e32 v1, v12, v44
	v_fmac_f32_e32 v1, v13, v45
	v_fmac_f32_e32 v1, v14, v46
	v_fmac_f32_e32 v1, v15, v47
	v_fmac_f32_e32 v1, v16, v48
	v_fmac_f32_e32 v1, v17, v49
	v_fmac_f32_e32 v1, v18, v50
	v_fmac_f32_e32 v1, v19, v51
	v_fmac_f32_e32 v1, v20, v52
	v_fmac_f32_e32 v1, v21, v53
	v_fmac_f32_e32 v1, v22, v54
	v_fmac_f32_e32 v1, v23, v55
	v_fmac_f32_e32 v1, v24, v56
	v_fmac_f32_e32 v1, v25, v57
	v_fmac_f32_e32 v1, v26, v58
	v_fmac_f32_e32 v1, v27, v59
	v_fmac_f32_e32 v1, v28, v60
	v_fmac_f32_e32 v1, v29, v61
	v_fmac_f32_e32 v1, v30, v62
	v_fmac_f32_e32 v1, v31, v63
	v_fmac_f32_e32 v1, v32, v64
	v_fmac_f32_e32 v1, v33, v65
	v_fmac_f32_e32 v1, v34, v66
	v_fmac_f32_e32 v1, v35, v67
	v_fmac_f32_e32 v1, v36, v68
	v_fmac_f32_e32 v1, v37, v69
	v_fmac_f32_e32 v1, v38, v70
	v_fmac_f32_e32 v1, v39, v71
	s_sub_u32 s26, s26, 1
	s_cmp_lg_u32 s26, 0
	s_cbranch_scc1 .Lb1_loop
	v_lshlrev_b32_e32 v2, 2, v129
	v_add_u32_e32 v2, 0x8000, v2
	ds_write_b32 v2, v1
	s_waitcnt lgkmcnt(0)
	s_barrier
	v_cmp_gt_u32_e32 vcc, 64, v129
	s_and_saveexec_b64 s[8:9], vcc
	s_cbranch_execz .Lb1_skip
	ds_read_b32 v8, v2 offset:0
	ds_read_b32 v9, v2 offset:256
	ds_read_b32 v10, v2 offset:512
	ds_read_b32 v11, v2 offset:768
	ds_read_b32 v12, v2 offset:1024
	ds_read_b32 v13, v2 offset:1280
	ds_read_b32 v14, v2 offset:1536
	ds_read_b32 v15, v2 offset:1792
	v_readlane_b32 s10, v253, 9
	v_readlane_b32 s11, v253, 10
	s_lshl_b32 s14, s4, 8
	s_waitcnt lgkmcnt(0)
	v_add_f32_e32 v8, v8, v9
	v_add_f32_e32 v8, v8, v10
	v_add_f32_e32 v8, v8, v11
	v_add_f32_e32 v8, v8, v12
	v_add_f32_e32 v8, v8, v13
	v_add_f32_e32 v8, v8, v14
	v_add_f32_e32 v8, v8, v15
	s_add_u32 s10, s10, s14
	s_addc_u32 s11, s11, 0
	s_nop 1
	global_store_dword v0, v8, s[10:11]
; DI bf16_t f2bf(float x) { unsigned r; asm("v_cvt_pk_bf16_f32 %0, %1, %1" : "=v"(r) : "v"(x)); return (bf16_t)(r & 0xffffu); }
; DI void conv_tile(const ConvD& c, int tn, int tk, float* lds) {
;     ...
; #pragma unroll
;     for (int i = 0; i < 8; ++i) lds[((tid >> 6) + 8 * i) * 65 + j] = tv[i];
;   }
;   __syncthreads();
;   {
;     const int kk = tid & 63;
; #pragma unroll
;     for (int i = 0; i < 8; ++i) {
;       const int j = (tid >> 6) + 8 * i;
;       c.dst[(size_t)(n0 + j) * c.K + k0 + kk] = f2bf(lds[kk * 65 + j]);
;     }
;   }
;   __syncthreads();
; DI void phase0(const Params& p, char* lds) {
;     ...
;   for (int w = blockIdx.x; w < 2 * CONV_PER_LAYER; w += gridDim.x) {
;     const int l = w / CONV_PER_LAYER; int ww = w % CONV_PER_LAYER; int id = 0;
; #pragma unroll
;     for (int i = 0; i < 14; ++i) { if (id == i && ww >= CONV_NT[i]) { ww -= CONV_NT[i]; id = i + 1; } }
;     const ConvD c = get_conv(p, l, id);
;     const int ntn = c.Nout >> 6;
;     conv_tile(c, ww % ntn, ww / ntn, (float*)lds);
;   }
.Lb1_skip:
	s_or_b64 exec, exec, s[8:9]
.LBB0_773:
	v_readlane_b32 s8, v253, 11
	v_readlane_b32 s9, v253, 12
	s_andn2_b64 vcc, exec, s[8:9]
	s_cbranch_vccnz .LBB0_863
	v_readlane_b32 s4, v254, 1
	s_branch .LBB0_781
.LBB0_780:
	s_or_b64 exec, exec, s[54:55]
	v_lshl_add_u32 v0, v2, 2, 0
	s_movk_i32 s15, 0x104
	v_mad_u64_u32 v[14:15], s[26:27], v3, s15, v[0:1]
	s_ashr_i32 s15, s14, 31
	s_lshl_b64 s[14:15], s[14:15], 1
	s_waitcnt vmcnt(0)
	ds_write_b32 v14, v5
	ds_write_b32 v14, v4 offset:2080
	ds_write_b32 v14, v8 offset:4160
	ds_write_b32 v14, v7 offset:6240
	ds_write_b32 v14, v10 offset:8320
	ds_write_b32 v14, v9 offset:10400
	ds_write_b32 v14, v12 offset:12480
	ds_write_b32 v14, v11 offset:14560
	s_add_u32 s8, s8, s14
	v_add_u32_e32 v7, s22, v3
	v_lshlrev_b32_e32 v1, 8, v2
	v_lshlrev_b32_e32 v4, 2, v3
	s_addc_u32 s9, s9, s15
	v_lshlrev_b32_e32 v130, 1, v2
	v_ashrrev_i32_e32 v2, 31, v7
	v_add3_u32 v6, v0, v1, v4
	v_lshl_add_u64 v[4:5], s[8:9], 0, v[130:131]
	v_mul_lo_u32 v8, s10, v2
	v_mul_lo_u32 v9, s11, v7
	v_mad_u64_u32 v[2:3], s[8:9], s10, v7, 0
	v_add3_u32 v3, v3, v8, v9
	s_waitcnt lgkmcnt(0)
	s_barrier
	ds_read2_b32 v[0:1], v6 offset1:8
	v_lshl_add_u64 v[2:3], v[2:3], 1, v[4:5]
	s_waitcnt lgkmcnt(0)
	v_cvt_pk_bf16_f32 v0, v0, v0
	global_store_short v[2:3], v0, off
	v_add_u32_e32 v2, 8, v7
	v_ashrrev_i32_e32 v0, 31, v2
	v_mul_lo_u32 v9, s10, v0
	v_mul_lo_u32 v10, s11, v2
	v_mad_u64_u32 v[2:3], s[8:9], s10, v2, 0
	v_add3_u32 v3, v3, v9, v10
	v_lshl_add_u64 v[2:3], v[2:3], 1, v[4:5]
	v_cvt_pk_bf16_f32 v8, v1, v1
	global_store_short v[2:3], v8, off
	v_add_u32_e32 v2, 16, v7
	v_ashrrev_i32_e32 v3, 31, v2
	v_mul_lo_u32 v8, s10, v3
	v_mul_lo_u32 v9, s11, v2
	v_mad_u64_u32 v[2:3], s[8:9], s10, v2, 0
	v_add3_u32 v3, v3, v8, v9
	ds_read2_b32 v[0:1], v6 offset0:16 offset1:24
	v_lshl_add_u64 v[2:3], v[2:3], 1, v[4:5]
	s_waitcnt lgkmcnt(0)
	v_cvt_pk_bf16_f32 v0, v0, v0
	global_store_short v[2:3], v0, off
	v_add_u32_e32 v2, 24, v7
	v_ashrrev_i32_e32 v0, 31, v2
	v_mul_lo_u32 v9, s10, v0
	v_mul_lo_u32 v10, s11, v2
	v_mad_u64_u32 v[2:3], s[8:9], s10, v2, 0
	v_add3_u32 v3, v3, v9, v10
	v_lshl_add_u64 v[2:3], v[2:3], 1, v[4:5]
	v_cvt_pk_bf16_f32 v8, v1, v1
	global_store_short v[2:3], v8, off
	v_add_u32_e32 v2, 32, v7
	v_ashrrev_i32_e32 v3, 31, v2
	v_mul_lo_u32 v8, s10, v3
	v_mul_lo_u32 v9, s11, v2
	v_mad_u64_u32 v[2:3], s[8:9], s10, v2, 0
	v_add3_u32 v3, v3, v8, v9
	ds_read2_b32 v[0:1], v6 offset0:32 offset1:40
	v_lshl_add_u64 v[2:3], v[2:3], 1, v[4:5]
	s_waitcnt lgkmcnt(0)
	v_cvt_pk_bf16_f32 v0, v0, v0
	global_store_short v[2:3], v0, off
	v_add_u32_e32 v2, 40, v7
	v_ashrrev_i32_e32 v0, 31, v2
	v_mul_lo_u32 v9, s10, v0
	v_mul_lo_u32 v10, s11, v2
	v_mad_u64_u32 v[2:3], s[8:9], s10, v2, 0
	v_add3_u32 v3, v3, v9, v10
	v_lshl_add_u64 v[2:3], v[2:3], 1, v[4:5]
	v_cvt_pk_bf16_f32 v8, v1, v1
	global_store_short v[2:3], v8, off
	v_add_u32_e32 v2, 48, v7
	v_ashrrev_i32_e32 v3, 31, v2
	ds_read2_b32 v[0:1], v6 offset0:48 offset1:56
	v_mul_lo_u32 v6, s10, v3
	v_mul_lo_u32 v8, s11, v2
	v_mad_u64_u32 v[2:3], s[8:9], s10, v2, 0
	v_add3_u32 v3, v3, v6, v8
	s_waitcnt lgkmcnt(0)
	v_cvt_pk_bf16_f32 v0, v0, v0
	v_lshl_add_u64 v[2:3], v[2:3], 1, v[4:5]
	global_store_short v[2:3], v0, off
	v_add_u32_e32 v0, 56, v7
	v_cvt_pk_bf16_f32 v2, v1, v1
	v_ashrrev_i32_e32 v1, 31, v0
	v_mul_lo_u32 v3, s10, v1
	v_mul_lo_u32 v6, s11, v0
	v_mad_u64_u32 v[0:1], s[8:9], s10, v0, 0
	v_add3_u32 v1, v1, v3, v6
	s_add_i32 s4, s4, s33
	v_lshl_add_u64 v[0:1], v[0:1], 1, v[4:5]
	s_cmpk_gt_i32 s4, 0x32df
	global_store_short v[0:1], v2, off
	s_barrier
	s_cbranch_scc1 .LBB0_863
